# on top of v14: half 0 (waves 0-3) runs its MLA MFMA block at s_setprio 1, reset to 0 before softmax
# speedup vs baseline: 1.0094x; 1.0094x over previous
.LBB0_866:
	s_sub_i32 s0, 0, s97
	s_add_i32 s0, s0, 0x10800
	v_lshl_add_u64 v[230:231], v[190:191], 1, s[76:77]
	s_add_i32 s1, s0, s54
	s_mov_b32 m0, s1
	s_nop 0
	global_load_lds_dwordx4 v[230:231], off
	v_lshl_add_u64 v[230:231], v[192:193], 1, s[76:77]
	s_add_i32 s0, s0, s71
	s_mov_b32 m0, s0
	s_nop 0
	global_load_lds_dwordx4 v[230:231], off
	s_setprio 1
.LBB0_867:
	s_waitcnt lgkmcnt(5)
	v_mfma_f32_32x32x16_bf16 v[98:113], v[82:85], v[114:117], v[66:81]
	s_waitcnt lgkmcnt(3)
	v_mfma_f32_32x32x16_bf16 v[82:97], v[210:213], v[114:117], v[66:81]
	ds_read_b128 v[210:213], v205 offset:96
	ds_read_b128 v[230:233], v205 offset:12896
	v_mfma_f32_32x32x16_bf16 v[98:113], v[206:209], v[118:121], v[98:113]
	s_waitcnt lgkmcnt(3)
	v_mfma_f32_32x32x16_bf16 v[82:97], v[222:225], v[118:121], v[82:97]
	ds_read_b128 v[206:209], v205 offset:128
	ds_read_b128 v[222:225], v205 offset:12928
	v_mfma_f32_32x32x16_bf16 v[98:113], v[218:221], v[122:125], v[98:113]
	s_waitcnt lgkmcnt(4)
	v_mfma_f32_32x32x16_bf16 v[82:97], v[226:229], v[122:125], v[82:97]
	ds_read_b128 v[218:221], v205 offset:160
	ds_read_b128 v[226:229], v205 offset:12960
	s_waitcnt lgkmcnt(5)
	v_mfma_f32_32x32x16_bf16 v[98:113], v[210:213], v[126:129], v[98:113]
	s_waitcnt lgkmcnt(4)
	v_mfma_f32_32x32x16_bf16 v[82:97], v[230:233], v[126:129], v[82:97]
	ds_read_b128 v[210:213], v205 offset:192
	ds_read_b128 v[230:233], v205 offset:12992
	s_waitcnt lgkmcnt(5)
	v_mfma_f32_32x32x16_bf16 v[98:113], v[206:209], v[130:133], v[98:113]
	s_waitcnt lgkmcnt(4)
	v_mfma_f32_32x32x16_bf16 v[82:97], v[222:225], v[130:133], v[82:97]
	ds_read_b128 v[206:209], v205 offset:224
	ds_read_b128 v[222:225], v205 offset:13024
	s_waitcnt lgkmcnt(5)
	v_mfma_f32_32x32x16_bf16 v[98:113], v[218:221], v[134:137], v[98:113]
	s_waitcnt lgkmcnt(4)
	v_mfma_f32_32x32x16_bf16 v[82:97], v[226:229], v[134:137], v[82:97]
	ds_read_b128 v[218:221], v205 offset:256
	ds_read_b128 v[226:229], v205 offset:13056
	s_waitcnt lgkmcnt(5)
	v_mfma_f32_32x32x16_bf16 v[98:113], v[210:213], v[138:141], v[98:113]
	s_waitcnt lgkmcnt(4)
	v_mfma_f32_32x32x16_bf16 v[82:97], v[230:233], v[138:141], v[82:97]
	ds_read_b128 v[210:213], v205 offset:288
	ds_read_b128 v[230:233], v205 offset:13088
	ds_read_b64_tr_b16 v[234:235], v214 offset:51200
	ds_read_b64_tr_b16 v[236:237], v214 offset:53248
	s_waitcnt lgkmcnt(7)
	v_mfma_f32_32x32x16_bf16 v[98:113], v[206:209], v[142:145], v[98:113]
	s_waitcnt lgkmcnt(6)
	v_mfma_f32_32x32x16_bf16 v[82:97], v[222:225], v[142:145], v[82:97]
	ds_read_b128 v[206:209], v205 offset:320
	ds_read_b128 v[222:225], v205 offset:13120
	ds_read_b64_tr_b16 v[238:239], v214 offset:55296
	ds_read_b64_tr_b16 v[240:241], v214 offset:57344
	s_waitcnt lgkmcnt(9)
	v_mfma_f32_32x32x16_bf16 v[98:113], v[218:221], v[146:149], v[98:113]
	s_waitcnt lgkmcnt(8)
	v_mfma_f32_32x32x16_bf16 v[82:97], v[226:229], v[146:149], v[82:97]
	ds_read_b128 v[218:221], v205 offset:352
	ds_read_b128 v[226:229], v205 offset:13152
	ds_read_b64_tr_b16 v[242:243], v214 offset:59392
	ds_read_b64_tr_b16 v[244:245], v214 offset:61440
	s_waitcnt lgkmcnt(11)
	v_mfma_f32_32x32x16_bf16 v[98:113], v[210:213], v[154:157], v[98:113]
	s_waitcnt lgkmcnt(10)
	v_mfma_f32_32x32x16_bf16 v[82:97], v[230:233], v[154:157], v[82:97]
	ds_read_b64_tr_b16 v[210:211], v214 offset:63488
	ds_read_b64_tr_b16 v[212:213], v215 offset:14336
	s_waitcnt lgkmcnt(9)
	v_mfma_f32_32x32x16_bf16 v[98:113], v[206:209], v[150:153], v[98:113]
	s_waitcnt lgkmcnt(8)
	v_mfma_f32_32x32x16_bf16 v[82:97], v[222:225], v[150:153], v[82:97]
	ds_read_b64_tr_b16 v[206:207], v214 offset:51712
	ds_read_b64_tr_b16 v[208:209], v214 offset:53760
	s_waitcnt lgkmcnt(7)
	v_mfma_f32_32x32x16_bf16 v[98:113], v[218:221], v[158:161], v[98:113]
	s_waitcnt lgkmcnt(6)
	v_mfma_f32_32x32x16_bf16 v[82:97], v[226:229], v[158:161], v[82:97]
	ds_read_b64_tr_b16 v[218:219], v214 offset:55808
	ds_read_b64_tr_b16 v[220:221], v214 offset:57856
	v_mfma_f32_32x32x16_bf16 v[50:65], v[162:165], v[234:237], v[50:65]
	ds_read_b64_tr_b16 v[222:223], v214 offset:59904
	ds_read_b64_tr_b16 v[224:225], v214 offset:61952
	v_mfma_f32_32x32x16_bf16 v[50:65], v[166:169], v[238:241], v[50:65]
	ds_read_b64_tr_b16 v[226:227], v214 offset:64000
	ds_read_b64_tr_b16 v[228:229], v215 offset:14848
	s_waitcnt lgkmcnt(10)
	v_mfma_f32_32x32x16_bf16 v[50:65], v[170:173], v[242:245], v[50:65]
	ds_read_b64_tr_b16 v[230:231], v214 offset:52224
	ds_read_b64_tr_b16 v[232:233], v214 offset:54272
	s_waitcnt lgkmcnt(10)
	v_mfma_f32_32x32x16_bf16 v[50:65], v[174:177], v[210:213], v[50:65]
	ds_read_b64_tr_b16 v[210:211], v214 offset:56320
	ds_read_b64_tr_b16 v[212:213], v214 offset:58368
	s_waitcnt lgkmcnt(10)
	v_mfma_f32_32x32x16_bf16 v[34:49], v[162:165], v[206:209], v[34:49]
	ds_read_b64_tr_b16 v[206:207], v214 offset:60416
	ds_read_b64_tr_b16 v[208:209], v214 offset:62464
	s_waitcnt lgkmcnt(10)
	v_mfma_f32_32x32x16_bf16 v[34:49], v[166:169], v[218:221], v[34:49]
	ds_read_b64_tr_b16 v[218:219], v214 offset:64512
	ds_read_b64_tr_b16 v[220:221], v215 offset:15360
	s_waitcnt lgkmcnt(10)
	v_mfma_f32_32x32x16_bf16 v[34:49], v[170:173], v[222:225], v[34:49]
	ds_read_b64_tr_b16 v[222:223], v214 offset:52736
	ds_read_b64_tr_b16 v[224:225], v214 offset:54784
	s_waitcnt lgkmcnt(10)
	v_mfma_f32_32x32x16_bf16 v[34:49], v[174:177], v[226:229], v[34:49]
	ds_read_b64_tr_b16 v[226:227], v214 offset:56832
	ds_read_b64_tr_b16 v[228:229], v214 offset:58880
	s_waitcnt lgkmcnt(10)
	v_mfma_f32_32x32x16_bf16 v[18:33], v[162:165], v[230:233], v[18:33]
	ds_read_b64_tr_b16 v[230:231], v214 offset:60928
	ds_read_b64_tr_b16 v[232:233], v214 offset:62976
	s_waitcnt lgkmcnt(10)
	v_mfma_f32_32x32x16_bf16 v[18:33], v[166:169], v[210:213], v[18:33]
	ds_read_b64_tr_b16 v[210:211], v214 offset:65024
	ds_read_b64_tr_b16 v[212:213], v215 offset:15872
	s_waitcnt lgkmcnt(10)
	v_mfma_f32_32x32x16_bf16 v[18:33], v[170:173], v[206:209], v[18:33]
	s_waitcnt lgkmcnt(8)
	v_mfma_f32_32x32x16_bf16 v[18:33], v[174:177], v[218:221], v[18:33]
	s_waitcnt lgkmcnt(6)
	v_mfma_f32_32x32x16_bf16 v[2:17], v[162:165], v[222:225], v[2:17]
	s_waitcnt lgkmcnt(4)
	v_mfma_f32_32x32x16_bf16 v[2:17], v[166:169], v[226:229], v[2:17]
	s_waitcnt lgkmcnt(2)
	v_mfma_f32_32x32x16_bf16 v[2:17], v[170:173], v[230:233], v[2:17]
	s_waitcnt lgkmcnt(0)
	v_mfma_f32_32x32x16_bf16 v[2:17], v[174:177], v[210:213], v[2:17]
	s_setprio 0
	s_and_b64 vcc, exec, s[4:5]
	s_cbranch_vccnz .LBB0_872
	s_waitcnt vmcnt(0) lgkmcnt(0)
	s_barrier
	s_cmpk_gt_u32 s53, 0x7d
	s_cbranch_scc1 .LBB0_870
	s_add_u32 s0, s74, s8
	s_addc_u32 s1, s33, s9
	s_add_u32 s0, s0, 0x36020000
	s_addc_u32 s1, s1, 0
	s_add_i32 s55, s55, 0
	v_lshl_add_u64 v[162:163], v[182:183], 1, s[0:1]
	s_add_i32 s62, s55, s54
	s_mov_b32 m0, s62
	s_nop 0
	global_load_lds_dwordx4 v[162:163], off
	v_lshl_add_u64 v[162:163], v[184:185], 1, s[0:1]
	s_add_i32 s62, s55, s71
	s_mov_b32 m0, s62
	s_nop 0
	global_load_lds_dwordx4 v[162:163], off
	v_lshl_add_u64 v[162:163], v[186:187], 1, s[0:1]
	s_add_i32 s55, s55, s70
	s_mov_b32 m0, s55
	s_nop 0
	global_load_lds_dwordx4 v[162:163], off

.LBB0_2810:
	s_sub_i32 s0, 0, s85
	s_add_i32 s0, s0, 0x10800
	v_lshl_add_u64 v[230:231], v[190:191], 1, s[76:77]
	s_add_i32 s1, s0, s70
	s_mov_b32 m0, s1
	s_nop 0
	global_load_lds_dwordx4 v[230:231], off
	v_lshl_add_u64 v[230:231], v[192:193], 1, s[76:77]
	s_add_i32 s0, s0, s71
	s_mov_b32 m0, s0
	s_nop 0
	global_load_lds_dwordx4 v[230:231], off
	s_setprio 1
.LBB0_2811:
	s_waitcnt lgkmcnt(5)
	v_mfma_f32_32x32x16_bf16 v[98:113], v[82:85], v[114:117], v[66:81]
	s_waitcnt lgkmcnt(3)
	v_mfma_f32_32x32x16_bf16 v[82:97], v[210:213], v[114:117], v[66:81]
	ds_read_b128 v[210:213], v205 offset:96
	ds_read_b128 v[230:233], v205 offset:12896
	v_mfma_f32_32x32x16_bf16 v[98:113], v[206:209], v[118:121], v[98:113]
	s_waitcnt lgkmcnt(3)
	v_mfma_f32_32x32x16_bf16 v[82:97], v[222:225], v[118:121], v[82:97]
	ds_read_b128 v[206:209], v205 offset:128
	ds_read_b128 v[222:225], v205 offset:12928
	v_mfma_f32_32x32x16_bf16 v[98:113], v[218:221], v[122:125], v[98:113]
	s_waitcnt lgkmcnt(4)
	v_mfma_f32_32x32x16_bf16 v[82:97], v[226:229], v[122:125], v[82:97]
	ds_read_b128 v[218:221], v205 offset:160
	ds_read_b128 v[226:229], v205 offset:12960
	s_waitcnt lgkmcnt(5)
	v_mfma_f32_32x32x16_bf16 v[98:113], v[210:213], v[126:129], v[98:113]
	s_waitcnt lgkmcnt(4)
	v_mfma_f32_32x32x16_bf16 v[82:97], v[230:233], v[126:129], v[82:97]
	ds_read_b128 v[210:213], v205 offset:192
	ds_read_b128 v[230:233], v205 offset:12992
	s_waitcnt lgkmcnt(5)
	v_mfma_f32_32x32x16_bf16 v[98:113], v[206:209], v[130:133], v[98:113]
	s_waitcnt lgkmcnt(4)
	v_mfma_f32_32x32x16_bf16 v[82:97], v[222:225], v[130:133], v[82:97]
	ds_read_b128 v[206:209], v205 offset:224
	ds_read_b128 v[222:225], v205 offset:13024
	s_waitcnt lgkmcnt(5)
	v_mfma_f32_32x32x16_bf16 v[98:113], v[218:221], v[134:137], v[98:113]
	s_waitcnt lgkmcnt(4)
	v_mfma_f32_32x32x16_bf16 v[82:97], v[226:229], v[134:137], v[82:97]
	ds_read_b128 v[218:221], v205 offset:256
	ds_read_b128 v[226:229], v205 offset:13056
	s_waitcnt lgkmcnt(5)
	v_mfma_f32_32x32x16_bf16 v[98:113], v[210:213], v[138:141], v[98:113]
	s_waitcnt lgkmcnt(4)
	v_mfma_f32_32x32x16_bf16 v[82:97], v[230:233], v[138:141], v[82:97]
	ds_read_b128 v[210:213], v205 offset:288
	ds_read_b128 v[230:233], v205 offset:13088
	ds_read_b64_tr_b16 v[234:235], v214 offset:51200
	ds_read_b64_tr_b16 v[236:237], v214 offset:53248
	s_waitcnt lgkmcnt(7)
	v_mfma_f32_32x32x16_bf16 v[98:113], v[206:209], v[142:145], v[98:113]
	s_waitcnt lgkmcnt(6)
	v_mfma_f32_32x32x16_bf16 v[82:97], v[222:225], v[142:145], v[82:97]
	ds_read_b128 v[206:209], v205 offset:320
	ds_read_b128 v[222:225], v205 offset:13120
	ds_read_b64_tr_b16 v[238:239], v214 offset:55296
	ds_read_b64_tr_b16 v[240:241], v214 offset:57344
	s_waitcnt lgkmcnt(9)
	v_mfma_f32_32x32x16_bf16 v[98:113], v[218:221], v[146:149], v[98:113]
	s_waitcnt lgkmcnt(8)
	v_mfma_f32_32x32x16_bf16 v[82:97], v[226:229], v[146:149], v[82:97]
	ds_read_b128 v[218:221], v205 offset:352
	ds_read_b128 v[226:229], v205 offset:13152
	ds_read_b64_tr_b16 v[242:243], v214 offset:59392
	ds_read_b64_tr_b16 v[244:245], v214 offset:61440
	s_waitcnt lgkmcnt(11)
	v_mfma_f32_32x32x16_bf16 v[98:113], v[210:213], v[154:157], v[98:113]
	s_waitcnt lgkmcnt(10)
	v_mfma_f32_32x32x16_bf16 v[82:97], v[230:233], v[154:157], v[82:97]
	ds_read_b64_tr_b16 v[210:211], v214 offset:63488
	ds_read_b64_tr_b16 v[212:213], v215 offset:14336
	s_waitcnt lgkmcnt(9)
	v_mfma_f32_32x32x16_bf16 v[98:113], v[206:209], v[150:153], v[98:113]
	s_waitcnt lgkmcnt(8)
	v_mfma_f32_32x32x16_bf16 v[82:97], v[222:225], v[150:153], v[82:97]
	ds_read_b64_tr_b16 v[206:207], v214 offset:51712
	ds_read_b64_tr_b16 v[208:209], v214 offset:53760
	s_waitcnt lgkmcnt(7)
	v_mfma_f32_32x32x16_bf16 v[98:113], v[218:221], v[158:161], v[98:113]
	s_waitcnt lgkmcnt(6)
	v_mfma_f32_32x32x16_bf16 v[82:97], v[226:229], v[158:161], v[82:97]
	ds_read_b64_tr_b16 v[218:219], v214 offset:55808
	ds_read_b64_tr_b16 v[220:221], v214 offset:57856
	v_mfma_f32_32x32x16_bf16 v[50:65], v[162:165], v[234:237], v[50:65]
	ds_read_b64_tr_b16 v[222:223], v214 offset:59904
	ds_read_b64_tr_b16 v[224:225], v214 offset:61952
	v_mfma_f32_32x32x16_bf16 v[50:65], v[166:169], v[238:241], v[50:65]
	ds_read_b64_tr_b16 v[226:227], v214 offset:64000
	ds_read_b64_tr_b16 v[228:229], v215 offset:14848
	s_waitcnt lgkmcnt(10)
	v_mfma_f32_32x32x16_bf16 v[50:65], v[170:173], v[242:245], v[50:65]
	ds_read_b64_tr_b16 v[230:231], v214 offset:52224
	ds_read_b64_tr_b16 v[232:233], v214 offset:54272
	s_waitcnt lgkmcnt(10)
	v_mfma_f32_32x32x16_bf16 v[50:65], v[174:177], v[210:213], v[50:65]
	ds_read_b64_tr_b16 v[210:211], v214 offset:56320
	ds_read_b64_tr_b16 v[212:213], v214 offset:58368
	s_waitcnt lgkmcnt(10)
	v_mfma_f32_32x32x16_bf16 v[34:49], v[162:165], v[206:209], v[34:49]
	ds_read_b64_tr_b16 v[206:207], v214 offset:60416
	ds_read_b64_tr_b16 v[208:209], v214 offset:62464
	s_waitcnt lgkmcnt(10)
	v_mfma_f32_32x32x16_bf16 v[34:49], v[166:169], v[218:221], v[34:49]
	ds_read_b64_tr_b16 v[218:219], v214 offset:64512
	ds_read_b64_tr_b16 v[220:221], v215 offset:15360
	s_waitcnt lgkmcnt(10)
	v_mfma_f32_32x32x16_bf16 v[34:49], v[170:173], v[222:225], v[34:49]
	ds_read_b64_tr_b16 v[222:223], v214 offset:52736
	ds_read_b64_tr_b16 v[224:225], v214 offset:54784
	s_waitcnt lgkmcnt(10)
	v_mfma_f32_32x32x16_bf16 v[34:49], v[174:177], v[226:229], v[34:49]
	ds_read_b64_tr_b16 v[226:227], v214 offset:56832
	ds_read_b64_tr_b16 v[228:229], v214 offset:58880
	s_waitcnt lgkmcnt(10)
	v_mfma_f32_32x32x16_bf16 v[18:33], v[162:165], v[230:233], v[18:33]
	ds_read_b64_tr_b16 v[230:231], v214 offset:60928
	ds_read_b64_tr_b16 v[232:233], v214 offset:62976
	s_waitcnt lgkmcnt(10)
	v_mfma_f32_32x32x16_bf16 v[18:33], v[166:169], v[210:213], v[18:33]
	ds_read_b64_tr_b16 v[210:211], v214 offset:65024
	ds_read_b64_tr_b16 v[212:213], v215 offset:15872
	s_waitcnt lgkmcnt(10)
	v_mfma_f32_32x32x16_bf16 v[18:33], v[170:173], v[206:209], v[18:33]
	s_waitcnt lgkmcnt(8)
	v_mfma_f32_32x32x16_bf16 v[18:33], v[174:177], v[218:221], v[18:33]
	s_waitcnt lgkmcnt(6)
	v_mfma_f32_32x32x16_bf16 v[2:17], v[162:165], v[222:225], v[2:17]
	s_waitcnt lgkmcnt(4)
	v_mfma_f32_32x32x16_bf16 v[2:17], v[166:169], v[226:229], v[2:17]
	s_waitcnt lgkmcnt(2)
	v_mfma_f32_32x32x16_bf16 v[2:17], v[170:173], v[230:233], v[2:17]
	s_waitcnt lgkmcnt(0)
	v_mfma_f32_32x32x16_bf16 v[2:17], v[174:177], v[210:213], v[2:17]
	s_setprio 0
	s_and_b64 vcc, exec, s[4:5]
	s_cbranch_vccnz .LBB0_2816
	s_waitcnt vmcnt(0) lgkmcnt(0)
	s_barrier
	s_cmpk_gt_u32 s82, 0x7d
	s_cbranch_scc1 .LBB0_2814
	s_add_u32 s0, s33, s8
	s_addc_u32 s1, s78, s9
	s_add_u32 s0, s0, 0x36020000
	s_addc_u32 s1, s1, 0
	s_add_i32 s62, s86, 0
	v_lshl_add_u64 v[162:163], v[182:183], 1, s[0:1]
	s_add_i32 s63, s62, s70
	s_mov_b32 m0, s63
	s_nop 0
	global_load_lds_dwordx4 v[162:163], off
	v_lshl_add_u64 v[162:163], v[184:185], 1, s[0:1]
	s_add_i32 s63, s62, s71
	s_mov_b32 m0, s63
	s_nop 0
	global_load_lds_dwordx4 v[162:163], off
	v_lshl_add_u64 v[162:163], v[186:187], 1, s[0:1]
	s_add_i32 s62, s62, s83
	s_mov_b32 m0, s62
	s_nop 0
	global_load_lds_dwordx4 v[162:163], off
